# v74 + P4 mlstm_out: the Q/K -> LDS wait chain of units with k>0 counts past the 16 newer C_k^T loads (LDS image and wave-0 gate scan no longer wait for them)
# speedup vs baseline: 1.0156x; 1.0137x over previous
.Lmy_p4_non:
	s_waitcnt vmcnt(17)
	v_ashrrev_i32_e32 v70, 5, v4
	v_ashrrev_i32_e32 v71, 31, v70
	v_lshlrev_b32_e32 v2, 4, v4
	v_lshl_add_u64 v[6:7], s[68:69], 0, v[70:71]
	v_and_b32_e32 v2, 0x1f0, v2
	v_lshl_add_u64 v[8:9], s[20:21], 0, v[2:3]
	v_lshlrev_b64 v[6:7], 11, v[6:7]
	v_lshl_add_u64 v[62:63], v[8:9], 0, v[6:7]
	v_lshl_add_u64 v[10:11], s[36:37], 0, v[2:3]
	v_add_co_u32_e32 v14, vcc, s80, v62
	v_lshl_add_u64 v[64:65], v[10:11], 0, v[6:7]
	s_nop 0
	v_addc_co_u32_e32 v15, vcc, 0, v63, vcc
	v_add_co_u32_e32 v18, vcc, s80, v64
	global_load_dwordx4 v[6:9], v[62:63], off
	global_load_dwordx4 v[10:13], v[64:65], off
	v_addc_co_u32_e32 v19, vcc, 0, v65, vcc
	v_add_co_u32_e32 v22, vcc, s46, v62
	global_load_dwordx4 v[14:17], v[14:15], off
	s_nop 0
	global_load_dwordx4 v[18:21], v[18:19], off
	v_addc_co_u32_e32 v23, vcc, 0, v63, vcc
	v_add_co_u32_e32 v26, vcc, s46, v64
	s_movk_i32 s0, 0x210
	s_nop 0
	v_addc_co_u32_e32 v27, vcc, 0, v65, vcc
	v_add_co_u32_e32 v30, vcc, s81, v62
	global_load_dwordx4 v[22:25], v[22:23], off
	s_nop 0
	global_load_dwordx4 v[26:29], v[26:27], off
	v_addc_co_u32_e32 v31, vcc, 0, v63, vcc
	v_add_co_u32_e32 v34, vcc, s81, v64
	v_mul_lo_u32 v5, v70, s0
	s_nop 0
	v_addc_co_u32_e32 v35, vcc, 0, v65, vcc
	v_add_co_u32_e32 v38, vcc, s47, v62
	global_load_dwordx4 v[30:33], v[30:31], off
	s_nop 0
	global_load_dwordx4 v[34:37], v[34:35], off
	v_addc_co_u32_e32 v39, vcc, 0, v63, vcc
	v_add_co_u32_e32 v42, vcc, s47, v64
	v_add3_u32 v2, v5, v2, 0
	s_nop 0
	v_addc_co_u32_e32 v43, vcc, 0, v65, vcc
	v_add_co_u32_e32 v46, vcc, s82, v62
	global_load_dwordx4 v[38:41], v[38:39], off
	s_nop 0
	global_load_dwordx4 v[42:45], v[42:43], off
	v_addc_co_u32_e32 v47, vcc, 0, v63, vcc
	v_add_co_u32_e32 v50, vcc, s82, v64
	v_add_u32_e32 v5, 0x10800, v2
	s_nop 0
	v_addc_co_u32_e32 v51, vcc, 0, v65, vcc
	v_add_co_u32_e32 v54, vcc, s83, v62
	global_load_dwordx4 v[46:49], v[46:47], off
	s_nop 0
	global_load_dwordx4 v[50:53], v[50:51], off
	v_addc_co_u32_e32 v55, vcc, 0, v63, vcc
	v_add_co_u32_e32 v58, vcc, s83, v64
	s_cmp_lg_u32 s33, 0
	s_nop 0
	v_addc_co_u32_e32 v59, vcc, 0, v65, vcc
	v_add_co_u32_e32 v62, vcc, s84, v62
	global_load_dwordx4 v[54:57], v[54:55], off
	s_nop 0
	global_load_dwordx4 v[58:61], v[58:59], off
	v_addc_co_u32_e32 v63, vcc, 0, v63, vcc
	v_add_co_u32_e32 v66, vcc, s84, v64
	s_cselect_b64 s[24:25], -1, 0
	s_nop 0
	v_addc_co_u32_e32 v67, vcc, 0, v65, vcc
	global_load_dwordx4 v[62:65], v[62:63], off
	s_nop 0
	global_load_dwordx4 v[66:69], v[66:67], off
	s_cmp_eq_u32 s33, 0
	s_cbranch_scc1 .Lmy_p4_noct
	s_or_b32 s0, s33, s29
	s_ashr_i32 s1, s0, 31
	s_lshl_b64 s[0:1], s[0:1], 17
	s_add_u32 s0, s75, s0
	s_addc_u32 s1, s76, s1
	v_and_b32_e32 v216, 63, v4
	v_lshlrev_b32_e32 v216, 4, v216
	v_mov_b32_e32 v217, 0
	v_lshl_add_u64 v[218:219], s[0:1], 0, v[216:217]
	v_lshl_add_u64 v[218:219], v[218:219], 0, s[38:39]
	s_movk_i32 s0, 0x1000
	v_add_co_u32_e32 v220, vcc, s0, v218
	global_load_dwordx4 v[84:87], v[218:219], off
	global_load_dwordx4 v[88:91], v[218:219], off offset:1024
	global_load_dwordx4 v[92:95], v[218:219], off offset:2048
	global_load_dwordx4 v[96:99], v[218:219], off offset:3072
	v_addc_co_u32_e32 v221, vcc, 0, v219, vcc
	global_load_dwordx4 v[100:103], v[220:221], off
	global_load_dwordx4 v[104:107], v[220:221], off offset:1024
	global_load_dwordx4 v[108:111], v[220:221], off offset:2048
	global_load_dwordx4 v[112:115], v[220:221], off offset:3072
	v_add_co_u32_e32 v220, vcc, 0x2000, v218
	s_nop 1
	v_addc_co_u32_e32 v221, vcc, 0, v219, vcc
	v_add_co_u32_e32 v218, vcc, 0x3000, v218
	global_load_dwordx4 v[116:119], v[220:221], off
	global_load_dwordx4 v[120:123], v[220:221], off offset:1024
	global_load_dwordx4 v[124:127], v[220:221], off offset:2048
	global_load_dwordx4 v[128:131], v[220:221], off offset:3072
	v_addc_co_u32_e32 v219, vcc, 0, v219, vcc
	global_load_dwordx4 v[132:135], v[218:219], off
	global_load_dwordx4 v[136:139], v[218:219], off offset:1024
	global_load_dwordx4 v[140:143], v[218:219], off offset:2048
	global_load_dwordx4 v[144:147], v[218:219], off offset:3072
	s_waitcnt vmcnt(31)
	ds_write_b128 v2, v[6:9]
	s_waitcnt vmcnt(30)
	ds_write_b128 v5, v[10:13]
	s_waitcnt vmcnt(29)
	ds_write_b128 v2, v[14:17] offset:8448
	s_waitcnt vmcnt(28)
	ds_write_b128 v5, v[18:21] offset:8448
	s_waitcnt vmcnt(27)
	ds_write_b128 v2, v[22:25] offset:16896
	s_waitcnt vmcnt(26)
	ds_write_b128 v5, v[26:29] offset:16896
	s_waitcnt vmcnt(25)
	ds_write_b128 v2, v[30:33] offset:25344
	s_waitcnt vmcnt(24)
	ds_write_b128 v5, v[34:37] offset:25344
	s_waitcnt vmcnt(23)
	ds_write_b128 v2, v[38:41] offset:33792
	s_waitcnt vmcnt(22)
	ds_write_b128 v5, v[42:45] offset:33792
	s_waitcnt vmcnt(21)
	ds_write_b128 v2, v[46:49] offset:42240
	s_waitcnt vmcnt(20)
	ds_write_b128 v5, v[50:53] offset:42240
	s_waitcnt vmcnt(19)
	ds_write_b128 v2, v[54:57] offset:50688
	s_waitcnt vmcnt(18)
	ds_write_b128 v5, v[58:61] offset:50688
	s_waitcnt vmcnt(17)
	ds_write_b128 v2, v[62:65] offset:59136
	s_waitcnt vmcnt(16)
	ds_write_b128 v5, v[66:69] offset:59136
	s_branch .Lmy_p4_join

.Lmy_p4_join:
	v_and_b32_e32 v5, 63, v4
